# all three rmsnorm loops (layer-0 input, layer-1 input, final) software-pipelined: next row's loads in flight during reduce/scale/store
# baseline (speedup 1.0000x reference)
; DI int otid() { int t = threadIdx.x; asm volatile("" : "+v"(t)); return t; }
; DI void rmsnorm_phase(const float* __restrict__ X, const float* __restrict__ g, bf16_t* __restrict__ H, float* __restrict__ OF) {
;   const int tid = otid(), lane = tid & 63;
;   const int gw = blockIdx.x * NWV + (tid >> 6), nw = gridDim.x * NWV;
;   for (int row = gw; row < T; row += nw) {
;     const float* xr = X + (size_t)row * D;
;     f32x4 v[8];
;     float ss = 0.f;
; #pragma unroll
;     for (int i = 0; i < 8; ++i) { v[i] = *(const f32x4*)(xr + lane * 4 + 256 * i); ss += v[i][0] * v[i][0] + v[i][1] * v[i][1] + v[i][2] * v[i][2] + v[i][3] * v[i][3]; }
;     ss = wave_sum(ss);
;     const float rstd = rsqrtf(ss * (1.f / D) + EPS);
; #pragma unroll
;     for (int i = 0; i < 8; ++i) {
;       const f32x4 gg = *(const f32x4*)(g + lane * 4 + 256 * i);
;       f32x4 o = v[i] * rstd * gg;
;       if (H) { u32x2 w; w.x = pk_bf16(o[0], o[1]); w.y = pk_bf16(o[2], o[3]); *(u32x2*)(H + (size_t)row * D + lane * 4 + 256 * i) = w; }
;       else *(f32x4*)(OF + (size_t)row * D + lane * 4 + 256 * i) = o;
;     }
;   }
; }
.LBB0_81:
	s_or_b64 exec, exec, s[0:1]
	v_mov_b32_e32 v34, v206
	s_lshl_b32 s0, s84, 3
	v_ashrrev_i32_e32 v1, 6, v34
	v_writelane_b32 v252, s0, 38
	v_add_u32_e32 v50, s0, v1
	s_movk_i32 s0, 0x4000
	v_cmp_gt_i32_e32 vcc, s0, v50
	v_mbcnt_lo_u32_b32 v207, -1, 0
	s_and_saveexec_b64 s[0:1], vcc
	s_cbranch_execz .LBB0_84
	v_lshlrev_b32_e32 v1, 4, v34
	v_and_b32_e32 v18, 0x3f0, v1
	v_mov_b32_e32 v19, 0
	v_lshl_add_u64 v[20:21], s[70:71], 0, v[18:19]
	s_movk_i32 s4, 0x1000
	v_add_co_u32_e32 v36, vcc, s4, v20
	global_load_dwordx4 v[2:5], v18, s[70:71]
	global_load_dwordx4 v[6:9], v18, s[70:71] offset:1024
	global_load_dwordx4 v[10:13], v18, s[70:71] offset:2048
	global_load_dwordx4 v[14:17], v18, s[70:71] offset:3072
	v_addc_co_u32_e32 v37, vcc, 0, v21, vcc
	global_load_dwordx4 v[18:21], v[36:37], off
	global_load_dwordx4 v[22:25], v[36:37], off offset:1024
	global_load_dwordx4 v[26:29], v[36:37], off offset:2048
	global_load_dwordx4 v[30:33], v[36:37], off offset:3072
	v_mbcnt_hi_u32_b32 v35, -1, v207
	v_and_b32_e32 v1, 64, v35
	v_add_u32_e32 v36, 64, v1
	v_xor_b32_e32 v1, 32, v35
	v_cmp_lt_i32_e32 vcc, v1, v36
	v_xor_b32_e32 v37, 16, v35
	s_load_dword s4, s[2:3], 0x10
	s_load_dword s6, s[2:3], 0x0
	v_cndmask_b32_e32 v1, v35, v1, vcc
	v_cmp_lt_i32_e32 vcc, v37, v36
	v_ashrrev_i32_e32 v51, 31, v50
	s_waitcnt lgkmcnt(0)
	s_lshr_b32 s4, s4, 16
	v_cndmask_b32_e32 v37, v35, v37, vcc
	v_lshlrev_b32_e32 v56, 2, v37
	v_xor_b32_e32 v37, 8, v35
	v_cmp_lt_i32_e32 vcc, v37, v36
	s_cmp_lg_u32 s4, 0
	s_cselect_b64 s[4:5], -1, 0
	v_cndmask_b32_e32 v37, v35, v37, vcc
	v_lshlrev_b32_e32 v57, 2, v37
	v_xor_b32_e32 v37, 4, v35
	v_cmp_lt_i32_e32 vcc, v37, v36
	v_and_b32_e32 v38, 63, v34
	s_cmp_lg_u64 s[4:5], 0
	v_cndmask_b32_e32 v37, v35, v37, vcc
	v_lshlrev_b32_e32 v58, 2, v37
	v_xor_b32_e32 v37, 2, v35
	v_cmp_lt_i32_e32 vcc, v37, v36
	s_addc_u32 s4, s6, 0
	s_mov_b64 s[6:7], 0x1000
	v_cndmask_b32_e32 v37, v35, v37, vcc
	v_lshlrev_b32_e32 v59, 2, v37
	v_xor_b32_e32 v37, 1, v35
	v_cmp_lt_i32_e32 vcc, v37, v36
	s_lshl_b32 s4, s4, 3
	s_ashr_i32 s5, s4, 31
	v_cndmask_b32_e32 v35, v35, v37, vcc
	v_lshlrev_b64 v[36:37], 13, v[50:51]
	v_lshl_or_b32 v36, v38, 4, v36
	v_lshlrev_b32_e32 v60, 2, v35
	v_lshl_add_u64 v[34:35], s[68:69], 0, v[36:37]
	v_lshl_add_u64 v[52:53], v[34:35], 0, s[6:7]
	v_lshlrev_b64 v[34:35], 12, v[50:51]
	v_lshl_or_b32 v34, v38, 3, v34
	v_lshl_add_u64 v[34:35], s[22:23], 0, v[34:35]
	s_mov_b64 s[8:9], 0x40c0000
	v_lshlrev_b32_e32 v1, 2, v1
	s_lshl_b64 s[6:7], s[4:5], 13
	v_lshl_add_u64 v[54:55], v[34:35], 0, s[8:9]
	s_lshl_b64 s[8:9], s[4:5], 12
	s_mov_b64 s[10:11], 0
	v_mov_b32_e32 v51, 0x358637bd
	s_mov_b32 s5, 0x800000
	s_movk_i32 s12, 0x3fff
	global_load_dwordx4 v[100:103], v[52:53], off
	global_load_dwordx4 v[104:107], v[52:53], off offset:1024
	global_load_dwordx4 v[108:111], v[52:53], off offset:2048
	global_load_dwordx4 v[112:115], v[52:53], off offset:3072
	global_load_dwordx4 v[116:119], v[52:53], off offset:-4096
	global_load_dwordx4 v[120:123], v[52:53], off offset:-3072
	global_load_dwordx4 v[124:127], v[52:53], off offset:-2048
	global_load_dwordx4 v[128:131], v[52:53], off offset:-1024
	s_waitcnt vmcnt(0)
	s_branch .Lrn0_body

; DI int otid() { int t = threadIdx.x; asm volatile("" : "+v"(t)); return t; }
; DI void rmsnorm_phase(const float* __restrict__ X, const float* __restrict__ g, bf16_t* __restrict__ H, float* __restrict__ OF) {
;   const int tid = otid(), lane = tid & 63;
;   const int gw = blockIdx.x * NWV + (tid >> 6), nw = gridDim.x * NWV;
;   for (int row = gw; row < T; row += nw) {
;     const float* xr = X + (size_t)row * D;
;     f32x4 v[8];
;     float ss = 0.f;
; #pragma unroll
;     for (int i = 0; i < 8; ++i) { v[i] = *(const f32x4*)(xr + lane * 4 + 256 * i); ss += v[i][0] * v[i][0] + v[i][1] * v[i][1] + v[i][2] * v[i][2] + v[i][3] * v[i][3]; }
;     ss = wave_sum(ss);
;     const float rstd = rsqrtf(ss * (1.f / D) + EPS);
; #pragma unroll
;     for (int i = 0; i < 8; ++i) {
;       const f32x4 gg = *(const f32x4*)(g + lane * 4 + 256 * i);
;       f32x4 o = v[i] * rstd * gg;
;       if (H) { u32x2 w; w.x = pk_bf16(o[0], o[1]); w.y = pk_bf16(o[2], o[3]); *(u32x2*)(H + (size_t)row * D + lane * 4 + 256 * i) = w; }
;       else *(f32x4*)(OF + (size_t)row * D + lane * 4 + 256 * i) = o;
;     }
;   }
; }
.Lrn0_body:
	v_mov_b64_e32 v[38:39], v[100:101]
	v_mov_b64_e32 v[40:41], v[102:103]
	v_mov_b64_e32 v[34:35], v[104:105]
	v_mov_b64_e32 v[36:37], v[106:107]
	v_mov_b64_e32 v[46:47], v[108:109]
	v_mov_b64_e32 v[48:49], v[110:111]
	v_mov_b64_e32 v[42:43], v[112:113]
	v_mov_b64_e32 v[44:45], v[114:115]
	v_mov_b64_e32 v[62:63], v[116:117]
	v_mov_b64_e32 v[64:65], v[118:119]
	v_mov_b64_e32 v[66:67], v[120:121]
	v_mov_b64_e32 v[68:69], v[122:123]
	v_mov_b64_e32 v[70:71], v[124:125]
	v_mov_b64_e32 v[72:73], v[126:127]
	v_mov_b64_e32 v[74:75], v[128:129]
	v_mov_b64_e32 v[76:77], v[130:131]
	v_add_u32_e32 v50, s4, v50
	v_cmp_lt_i32_e32 vcc, s12, v50
	s_or_b64 s[10:11], vcc, s[10:11]
	v_lshl_add_u64 v[98:99], v[52:53], 0, s[6:7]
	v_cndmask_b32_e32 v52, v98, v52, vcc
	v_cndmask_b32_e32 v53, v99, v53, vcc
	global_load_dwordx4 v[100:103], v[52:53], off
	global_load_dwordx4 v[104:107], v[52:53], off offset:1024
	global_load_dwordx4 v[108:111], v[52:53], off offset:2048
	global_load_dwordx4 v[112:115], v[52:53], off offset:3072
	global_load_dwordx4 v[116:119], v[52:53], off offset:-4096
	global_load_dwordx4 v[120:123], v[52:53], off offset:-3072
	global_load_dwordx4 v[124:127], v[52:53], off offset:-2048
	global_load_dwordx4 v[128:131], v[52:53], off offset:-1024
	v_mov_b32_e32 v80, v39
	v_mov_b32_e32 v81, v35
	v_mov_b32_e32 v78, v38
	v_mov_b32_e32 v79, v34
	v_mul_f32_e32 v61, v63, v63
	v_mul_f32_e32 v94, v67, v67
	v_mul_f32_e32 v95, v71, v71
	v_fmac_f32_e32 v61, v62, v62
	v_fmac_f32_e32 v94, v66, v66
	v_mul_f32_e32 v96, v75, v75
	v_fmac_f32_e32 v95, v70, v70
	v_fmac_f32_e32 v61, v64, v64
	v_fmac_f32_e32 v94, v68, v68
	v_pk_mul_f32 v[80:81], v[80:81], v[80:81]
	v_fmac_f32_e32 v96, v74, v74
	v_fmac_f32_e32 v95, v72, v72
	v_fmac_f32_e32 v61, v65, v65
	v_fmac_f32_e32 v94, v69, v69
	v_mov_b32_e32 v84, v47
	v_mov_b32_e32 v85, v43
	v_mov_b32_e32 v86, v40
	v_mov_b32_e32 v87, v36
	v_pk_fma_f32 v[78:79], v[78:79], v[78:79], v[80:81]
	v_fmac_f32_e32 v96, v76, v76
	v_fmac_f32_e32 v95, v73, v73
	v_add_f32_e32 v61, v61, v94
	v_mov_b32_e32 v82, v46
	v_mov_b32_e32 v83, v42
	v_mov_b32_e32 v90, v41
	v_mov_b32_e32 v91, v37
	v_pk_mul_f32 v[84:85], v[84:85], v[84:85]
	v_pk_fma_f32 v[78:79], v[86:87], v[86:87], v[78:79]
	v_fmac_f32_e32 v96, v77, v77
	v_add_f32_e32 v61, v61, v95
	v_mov_b32_e32 v88, v48
	v_mov_b32_e32 v89, v44
	v_pk_fma_f32 v[80:81], v[82:83], v[82:83], v[84:85]
	v_pk_fma_f32 v[78:79], v[90:91], v[90:91], v[78:79]
	v_add_f32_e32 v61, v61, v96
	v_mov_b32_e32 v92, v49
	v_mov_b32_e32 v93, v45
	v_pk_fma_f32 v[80:81], v[88:89], v[88:89], v[80:81]
	v_add_f32_e32 v61, v61, v78
	v_pk_fma_f32 v[80:81], v[92:93], v[92:93], v[80:81]
	v_add_f32_e32 v61, v61, v79
	v_add_f32_e32 v61, v61, v80
	v_add_f32_e32 v61, v61, v81
	ds_bpermute_b32 v78, v1, v61
	s_waitcnt lgkmcnt(0)
	v_add_f32_e32 v61, v61, v78
	ds_bpermute_b32 v78, v56, v61
	s_waitcnt lgkmcnt(0)
	v_add_f32_e32 v61, v61, v78
	ds_bpermute_b32 v78, v57, v61
	s_waitcnt lgkmcnt(0)
	v_add_f32_e32 v61, v61, v78
	ds_bpermute_b32 v78, v58, v61
	s_waitcnt lgkmcnt(0)
	v_add_f32_e32 v61, v61, v78
	ds_bpermute_b32 v78, v59, v61
	s_waitcnt lgkmcnt(0)
	v_add_f32_e32 v61, v61, v78
	ds_bpermute_b32 v78, v60, v61
	s_waitcnt lgkmcnt(0)
	v_add_f32_e32 v61, v61, v78
	v_fmamk_f32 v61, v61, 0x3a000000, v51
	v_mul_f32_e32 v78, 0x4b800000, v61
	v_cmp_gt_f32_e32 vcc, s5, v61
	s_nop 1
	v_cndmask_b32_e32 v61, v61, v78, vcc
	v_rsq_f32_e32 v61, v61
	s_nop 0
	v_mul_f32_e32 v78, 0x45800000, v61
	v_cndmask_b32_e32 v78, v61, v78, vcc
	v_pk_mul_f32 v[62:63], v[62:63], v[78:79] op_sel_hi:[1,0]
	v_pk_mul_f32 v[64:65], v[64:65], v[78:79] op_sel_hi:[1,0]
	v_pk_mul_f32 v[66:67], v[66:67], v[78:79] op_sel_hi:[1,0]
	v_pk_mul_f32 v[68:69], v[68:69], v[78:79] op_sel_hi:[1,0]
	v_pk_mul_f32 v[70:71], v[70:71], v[78:79] op_sel_hi:[1,0]
	v_pk_mul_f32 v[72:73], v[72:73], v[78:79] op_sel_hi:[1,0]
	v_pk_mul_f32 v[74:75], v[74:75], v[78:79] op_sel_hi:[1,0]
	v_pk_mul_f32 v[76:77], v[76:77], v[78:79] op_sel_hi:[1,0]
	v_pk_mul_f32 v[38:39], v[38:39], v[78:79] op_sel_hi:[1,0]
	v_pk_mul_f32 v[40:41], v[40:41], v[78:79] op_sel_hi:[1,0]
	v_pk_mul_f32 v[34:35], v[34:35], v[78:79] op_sel_hi:[1,0]
	v_pk_mul_f32 v[36:37], v[36:37], v[78:79] op_sel_hi:[1,0]
	v_pk_mul_f32 v[46:47], v[46:47], v[78:79] op_sel_hi:[1,0]
	v_pk_mul_f32 v[48:49], v[48:49], v[78:79] op_sel_hi:[1,0]
	v_pk_mul_f32 v[42:43], v[42:43], v[78:79] op_sel_hi:[1,0]
	v_pk_mul_f32 v[44:45], v[44:45], v[78:79] op_sel_hi:[1,0]
	v_pk_mul_f32 v[64:65], v[4:5], v[64:65]
	v_pk_mul_f32 v[62:63], v[2:3], v[62:63]
	v_pk_mul_f32 v[68:69], v[8:9], v[68:69]
	v_pk_mul_f32 v[66:67], v[6:7], v[66:67]
	v_pk_mul_f32 v[72:73], v[12:13], v[72:73]
	v_pk_mul_f32 v[70:71], v[10:11], v[70:71]
	v_pk_mul_f32 v[76:77], v[16:17], v[76:77]
	v_pk_mul_f32 v[74:75], v[14:15], v[74:75]
	v_pk_mul_f32 v[40:41], v[20:21], v[40:41]
	v_pk_mul_f32 v[38:39], v[18:19], v[38:39]
	v_pk_mul_f32 v[36:37], v[24:25], v[36:37]
	v_pk_mul_f32 v[34:35], v[22:23], v[34:35]
	v_pk_mul_f32 v[48:49], v[28:29], v[48:49]
	v_pk_mul_f32 v[46:47], v[26:27], v[46:47]
	v_pk_mul_f32 v[44:45], v[32:33], v[44:45]
	v_pk_mul_f32 v[42:43], v[30:31], v[42:43]
	v_cvt_pk_bf16_f32 v62, v62, v63
	v_cvt_pk_bf16_f32 v63, v64, v65
	v_cvt_pk_bf16_f32 v64, v66, v67
	v_cvt_pk_bf16_f32 v65, v68, v69
	v_cvt_pk_bf16_f32 v66, v70, v71
	v_cvt_pk_bf16_f32 v67, v72, v73
	v_cvt_pk_bf16_f32 v68, v74, v75
	v_cvt_pk_bf16_f32 v69, v76, v77
	v_cvt_pk_bf16_f32 v38, v38, v39
	v_cvt_pk_bf16_f32 v39, v40, v41
	v_cvt_pk_bf16_f32 v34, v34, v35
	v_cvt_pk_bf16_f32 v35, v36, v37
	v_cvt_pk_bf16_f32 v36, v46, v47
	v_cvt_pk_bf16_f32 v37, v48, v49
	v_cvt_pk_bf16_f32 v40, v42, v43
	v_cvt_pk_bf16_f32 v41, v44, v45
	global_store_dwordx2 v[54:55], v[62:63], off
	global_store_dwordx2 v[54:55], v[64:65], off offset:512
	global_store_dwordx2 v[54:55], v[66:67], off offset:1024
	global_store_dwordx2 v[54:55], v[68:69], off offset:1536
	global_store_dwordx2 v[54:55], v[38:39], off offset:2048
	global_store_dwordx2 v[54:55], v[34:35], off offset:2560
	global_store_dwordx2 v[54:55], v[36:37], off offset:3072
	global_store_dwordx2 v[54:55], v[40:41], off offset:3584
	v_lshl_add_u64 v[54:55], v[54:55], 0, s[8:9]
	s_andn2_b64 exec, exec, s[10:11]
	s_cbranch_execnz .LBB0_83

; DI int otid() { int t = threadIdx.x; asm volatile("" : "+v"(t)); return t; }
; DI void rmsnorm_phase(const float* __restrict__ X, const float* __restrict__ g, bf16_t* __restrict__ H, float* __restrict__ OF) {
;   const int tid = otid(), lane = tid & 63;
;   const int gw = blockIdx.x * NWV + (tid >> 6), nw = gridDim.x * NWV;
;   for (int row = gw; row < T; row += nw) {
;     const float* xr = X + (size_t)row * D;
;     f32x4 v[8];
;     float ss = 0.f;
; #pragma unroll
;     for (int i = 0; i < 8; ++i) { v[i] = *(const f32x4*)(xr + lane * 4 + 256 * i); ss += v[i][0] * v[i][0] + v[i][1] * v[i][1] + v[i][2] * v[i][2] + v[i][3] * v[i][3]; }
;     ss = wave_sum(ss);
;     const float rstd = rsqrtf(ss * (1.f / D) + EPS);
; #pragma unroll
;     for (int i = 0; i < 8; ++i) {
;       const f32x4 gg = *(const f32x4*)(g + lane * 4 + 256 * i);
;       f32x4 o = v[i] * rstd * gg;
;       if (H) { u32x2 w; w.x = pk_bf16(o[0], o[1]); w.y = pk_bf16(o[2], o[3]); *(u32x2*)(H + (size_t)row * D + lane * 4 + 256 * i) = w; }
;       else *(f32x4*)(OF + (size_t)row * D + lane * 4 + 256 * i) = o;
;     }
;   }
; }
.LBB0_819:
	s_or_b64 exec, exec, s[0:1]
	v_mov_b32_e32 v32, v206
	s_waitcnt lgkmcnt(0)
	s_barrier
	v_readlane_b32 s0, v252, 38
	v_ashrrev_i32_e32 v0, 6, v32
	s_lshl_b32 s26, s96, 3
	v_add_u32_e32 v48, s0, v0
	s_movk_i32 s0, 0x4000
	v_cmp_gt_i32_e32 vcc, s0, v48
	s_and_saveexec_b64 s[0:1], vcc
	s_cbranch_execz .LBB0_822
	v_lshlrev_b32_e32 v0, 4, v32
	v_and_b32_e32 v0, 0x3f0, v0
	v_mov_b32_e32 v1, 0
	v_lshl_add_u64 v[0:1], s[70:71], 0, v[0:1]
	s_mov_b64 s[2:3], 0x2000
	v_lshl_add_u64 v[34:35], v[0:1], 0, s[2:3]
	s_movk_i32 s2, 0x3000
	v_add_co_u32_e32 v36, vcc, s2, v0
	v_mbcnt_hi_u32_b32 v33, -1, v207
	s_nop 0
	v_addc_co_u32_e32 v37, vcc, 0, v1, vcc
	global_load_dwordx4 v[0:3], v[34:35], off offset:1024
	global_load_dwordx4 v[4:7], v[34:35], off offset:2048
	global_load_dwordx4 v[8:11], v[36:37], off offset:-4096
	global_load_dwordx4 v[12:15], v[34:35], off offset:3072
	global_load_dwordx4 v[16:19], v[36:37], off
	global_load_dwordx4 v[20:23], v[36:37], off offset:1024
	global_load_dwordx4 v[24:27], v[36:37], off offset:2048
	global_load_dwordx4 v[28:31], v[36:37], off offset:3072
	v_and_b32_e32 v34, 64, v33
	v_add_u32_e32 v34, 64, v34
	v_xor_b32_e32 v35, 32, v33
	v_cmp_lt_i32_e32 vcc, v35, v34
	v_ashrrev_i32_e32 v49, 31, v48
	v_and_b32_e32 v36, 63, v32
	v_cndmask_b32_e32 v35, v33, v35, vcc
	v_lshlrev_b32_e32 v54, 2, v35
	v_xor_b32_e32 v35, 16, v33
	v_cmp_lt_i32_e32 vcc, v35, v34
	s_mov_b64 s[2:3], 0x1000
	s_ashr_i32 s27, s26, 31
	v_cndmask_b32_e32 v35, v33, v35, vcc
	v_lshlrev_b32_e32 v55, 2, v35
	v_xor_b32_e32 v35, 8, v33
	v_cmp_lt_i32_e32 vcc, v35, v34
	s_mov_b64 s[6:7], 0x40c0000
	s_mov_b64 s[8:9], 0
	v_cndmask_b32_e32 v35, v33, v35, vcc
	v_lshlrev_b32_e32 v56, 2, v35
	v_xor_b32_e32 v35, 4, v33
	v_cmp_lt_i32_e32 vcc, v35, v34
	s_mov_b32 s10, 0x800000
	s_movk_i32 s11, 0x3fff
	v_cndmask_b32_e32 v35, v33, v35, vcc
	v_lshlrev_b32_e32 v57, 2, v35
	v_xor_b32_e32 v35, 2, v33
	v_cmp_lt_i32_e32 vcc, v35, v34
	s_nop 1
	v_cndmask_b32_e32 v35, v33, v35, vcc
	v_lshlrev_b32_e32 v58, 2, v35
	v_xor_b32_e32 v35, 1, v33
	v_cmp_lt_i32_e32 vcc, v35, v34
	s_nop 1
	v_cndmask_b32_e32 v33, v33, v35, vcc
	v_lshlrev_b64 v[34:35], 13, v[48:49]
	v_lshl_or_b32 v34, v36, 4, v34
	v_lshlrev_b32_e32 v59, 2, v33
	v_lshl_add_u64 v[32:33], s[20:21], 0, v[34:35]
	v_lshl_add_u64 v[50:51], v[32:33], 0, s[2:3]
	v_lshlrev_b64 v[32:33], 12, v[48:49]
	v_lshl_or_b32 v32, v36, 3, v32
	v_lshl_add_u64 v[32:33], s[22:23], 0, v[32:33]
	s_lshl_b64 s[2:3], s[26:27], 13
	v_lshl_add_u64 v[52:53], v[32:33], 0, s[6:7]
	s_lshl_b64 s[6:7], s[26:27], 12
	v_mov_b32_e32 v49, 0x358637bd
	global_load_dwordx4 v[100:103], v[50:51], off offset:-4096
	global_load_dwordx4 v[104:107], v[50:51], off offset:-3072
	global_load_dwordx4 v[108:111], v[50:51], off offset:-2048
	global_load_dwordx4 v[112:115], v[50:51], off offset:-1024
	global_load_dwordx4 v[116:119], v[50:51], off
	global_load_dwordx4 v[120:123], v[50:51], off offset:1024
	global_load_dwordx4 v[124:127], v[50:51], off offset:2048
	global_load_dwordx4 v[128:131], v[50:51], off offset:3072
	s_waitcnt vmcnt(0)
	s_branch .Lrn7_body

; DI int otid() { int t = threadIdx.x; asm volatile("" : "+v"(t)); return t; }
; DI void rmsnorm_phase(const float* __restrict__ X, const float* __restrict__ g, bf16_t* __restrict__ H, float* __restrict__ OF) {
;   const int tid = otid(), lane = tid & 63;
;   const int gw = blockIdx.x * NWV + (tid >> 6), nw = gridDim.x * NWV;
;   for (int row = gw; row < T; row += nw) {
;     const float* xr = X + (size_t)row * D;
;     f32x4 v[8];
;     float ss = 0.f;
; #pragma unroll
;     for (int i = 0; i < 8; ++i) { v[i] = *(const f32x4*)(xr + lane * 4 + 256 * i); ss += v[i][0] * v[i][0] + v[i][1] * v[i][1] + v[i][2] * v[i][2] + v[i][3] * v[i][3]; }
;     ss = wave_sum(ss);
;     const float rstd = rsqrtf(ss * (1.f / D) + EPS);
; #pragma unroll
;     for (int i = 0; i < 8; ++i) {
;       const f32x4 gg = *(const f32x4*)(g + lane * 4 + 256 * i);
;       f32x4 o = v[i] * rstd * gg;
;       if (H) { u32x2 w; w.x = pk_bf16(o[0], o[1]); w.y = pk_bf16(o[2], o[3]); *(u32x2*)(H + (size_t)row * D + lane * 4 + 256 * i) = w; }
;       else *(f32x4*)(OF + (size_t)row * D + lane * 4 + 256 * i) = o;
;     }
;   }
; }
.Lrn7_body:
	v_mov_b64_e32 v[32:33], v[100:101]
	v_mov_b64_e32 v[34:35], v[102:103]
	v_mov_b64_e32 v[36:37], v[104:105]
	v_mov_b64_e32 v[38:39], v[106:107]
	v_mov_b64_e32 v[40:41], v[108:109]
	v_mov_b64_e32 v[42:43], v[110:111]
	v_mov_b64_e32 v[44:45], v[112:113]
	v_mov_b64_e32 v[46:47], v[114:115]
	v_mov_b64_e32 v[60:61], v[116:117]
	v_mov_b64_e32 v[62:63], v[118:119]
	v_mov_b64_e32 v[64:65], v[120:121]
	v_mov_b64_e32 v[66:67], v[122:123]
	v_mov_b64_e32 v[68:69], v[124:125]
	v_mov_b64_e32 v[70:71], v[126:127]
	v_mov_b64_e32 v[72:73], v[128:129]
	v_mov_b64_e32 v[74:75], v[130:131]
	v_add_u32_e32 v48, s26, v48
	v_cmp_lt_i32_e32 vcc, s11, v48
	s_or_b64 s[8:9], vcc, s[8:9]
	v_lshl_add_u64 v[98:99], v[50:51], 0, s[2:3]
	v_cndmask_b32_e32 v50, v98, v50, vcc
	v_cndmask_b32_e32 v51, v99, v51, vcc
	global_load_dwordx4 v[100:103], v[50:51], off offset:-4096
	global_load_dwordx4 v[104:107], v[50:51], off offset:-3072
	global_load_dwordx4 v[108:111], v[50:51], off offset:-2048
	global_load_dwordx4 v[112:115], v[50:51], off offset:-1024
	global_load_dwordx4 v[116:119], v[50:51], off
	global_load_dwordx4 v[120:123], v[50:51], off offset:1024
	global_load_dwordx4 v[124:127], v[50:51], off offset:2048
	global_load_dwordx4 v[128:131], v[50:51], off offset:3072
	v_mul_f32_e32 v92, v33, v33
	v_mul_f32_e32 v93, v37, v37
	v_mul_f32_e32 v94, v41, v41
	v_fmac_f32_e32 v92, v32, v32
	v_mov_b32_e32 v78, v61
	v_mov_b32_e32 v79, v65
	v_fmac_f32_e32 v93, v36, v36
	v_mul_f32_e32 v95, v45, v45
	v_mov_b32_e32 v76, v60
	v_mov_b32_e32 v77, v64
	v_fmac_f32_e32 v94, v40, v40
	v_pk_mul_f32 v[78:79], v[78:79], v[78:79]
	v_fmac_f32_e32 v92, v34, v34
	v_fmac_f32_e32 v93, v38, v38
	v_mov_b32_e32 v80, v62
	v_mov_b32_e32 v81, v66
	v_fmac_f32_e32 v95, v44, v44
	v_fmac_f32_e32 v94, v42, v42
	v_pk_fma_f32 v[76:77], v[76:77], v[76:77], v[78:79]
	v_fmac_f32_e32 v92, v35, v35
	v_fmac_f32_e32 v93, v39, v39
	v_mov_b32_e32 v86, v69
	v_mov_b32_e32 v87, v73
	v_fmac_f32_e32 v95, v46, v46
	v_fmac_f32_e32 v94, v43, v43
	v_pk_fma_f32 v[76:77], v[80:81], v[80:81], v[76:77]
	v_add_f32_e32 v80, v92, v93
	v_mov_b32_e32 v82, v63
	v_mov_b32_e32 v83, v67
	v_mov_b32_e32 v84, v68
	v_mov_b32_e32 v85, v72
	v_pk_mul_f32 v[86:87], v[86:87], v[86:87]
	v_fmac_f32_e32 v95, v47, v47
	v_add_f32_e32 v80, v80, v94
	v_mov_b32_e32 v88, v70
	v_mov_b32_e32 v89, v74
	v_pk_fma_f32 v[78:79], v[84:85], v[84:85], v[86:87]
	v_pk_fma_f32 v[76:77], v[82:83], v[82:83], v[76:77]
	v_add_f32_e32 v80, v80, v95
	v_mov_b32_e32 v90, v71
	v_mov_b32_e32 v91, v75
	v_pk_fma_f32 v[78:79], v[88:89], v[88:89], v[78:79]
	v_add_f32_e32 v76, v80, v76
	v_pk_fma_f32 v[78:79], v[90:91], v[90:91], v[78:79]
	v_add_f32_e32 v76, v76, v77
	v_add_f32_e32 v76, v76, v78
	v_add_f32_e32 v76, v76, v79
	ds_bpermute_b32 v77, v54, v76
	s_waitcnt lgkmcnt(0)
	v_add_f32_e32 v76, v76, v77
	ds_bpermute_b32 v77, v55, v76
	s_waitcnt lgkmcnt(0)
	v_add_f32_e32 v76, v76, v77
	ds_bpermute_b32 v77, v56, v76
	s_waitcnt lgkmcnt(0)
	v_add_f32_e32 v76, v76, v77
	ds_bpermute_b32 v77, v57, v76
	s_waitcnt lgkmcnt(0)
	v_add_f32_e32 v76, v76, v77
	ds_bpermute_b32 v77, v58, v76
	s_waitcnt lgkmcnt(0)
	v_add_f32_e32 v76, v76, v77
	ds_bpermute_b32 v77, v59, v76
	s_waitcnt lgkmcnt(0)
	v_add_f32_e32 v76, v76, v77
	v_fmamk_f32 v76, v76, 0x3a000000, v49
	v_mul_f32_e32 v77, 0x4b800000, v76
	v_cmp_gt_f32_e32 vcc, s10, v76
	s_nop 1
	v_cndmask_b32_e32 v76, v76, v77, vcc
	v_rsq_f32_e32 v76, v76
	s_nop 0
	v_mul_f32_e32 v77, 0x45800000, v76
	v_cndmask_b32_e32 v76, v76, v77, vcc
	v_pk_mul_f32 v[32:33], v[32:33], v[76:77] op_sel_hi:[1,0]
	v_pk_mul_f32 v[34:35], v[34:35], v[76:77] op_sel_hi:[1,0]
	v_pk_mul_f32 v[36:37], v[36:37], v[76:77] op_sel_hi:[1,0]
	v_pk_mul_f32 v[38:39], v[38:39], v[76:77] op_sel_hi:[1,0]
	v_pk_mul_f32 v[40:41], v[40:41], v[76:77] op_sel_hi:[1,0]
	v_pk_mul_f32 v[42:43], v[42:43], v[76:77] op_sel_hi:[1,0]
	v_pk_mul_f32 v[44:45], v[44:45], v[76:77] op_sel_hi:[1,0]
	v_pk_mul_f32 v[46:47], v[46:47], v[76:77] op_sel_hi:[1,0]
	v_pk_mul_f32 v[60:61], v[60:61], v[76:77] op_sel_hi:[1,0]
	v_pk_mul_f32 v[62:63], v[62:63], v[76:77] op_sel_hi:[1,0]
	v_pk_mul_f32 v[64:65], v[64:65], v[76:77] op_sel_hi:[1,0]
	v_pk_mul_f32 v[66:67], v[66:67], v[76:77] op_sel_hi:[1,0]
	v_pk_mul_f32 v[68:69], v[68:69], v[76:77] op_sel_hi:[1,0]
	v_pk_mul_f32 v[70:71], v[70:71], v[76:77] op_sel_hi:[1,0]
	v_pk_mul_f32 v[72:73], v[72:73], v[76:77] op_sel_hi:[1,0]
	v_pk_mul_f32 v[74:75], v[74:75], v[76:77] op_sel_hi:[1,0]
	v_pk_mul_f32 v[34:35], v[10:11], v[34:35]
	v_pk_mul_f32 v[32:33], v[8:9], v[32:33]
	v_pk_mul_f32 v[38:39], v[2:3], v[38:39]
	v_pk_mul_f32 v[36:37], v[0:1], v[36:37]
	v_pk_mul_f32 v[42:43], v[6:7], v[42:43]
	v_pk_mul_f32 v[40:41], v[4:5], v[40:41]
	v_pk_mul_f32 v[46:47], v[14:15], v[46:47]
	v_pk_mul_f32 v[44:45], v[12:13], v[44:45]
	v_pk_mul_f32 v[62:63], v[18:19], v[62:63]
	v_pk_mul_f32 v[60:61], v[16:17], v[60:61]
	v_pk_mul_f32 v[66:67], v[22:23], v[66:67]
	v_pk_mul_f32 v[64:65], v[20:21], v[64:65]
	v_pk_mul_f32 v[70:71], v[26:27], v[70:71]
	v_pk_mul_f32 v[68:69], v[24:25], v[68:69]
	v_pk_mul_f32 v[74:75], v[30:31], v[74:75]
	v_pk_mul_f32 v[72:73], v[28:29], v[72:73]
	v_cvt_pk_bf16_f32 v32, v32, v33
	v_cvt_pk_bf16_f32 v33, v34, v35
	v_cvt_pk_bf16_f32 v34, v36, v37
	v_cvt_pk_bf16_f32 v35, v38, v39
	v_cvt_pk_bf16_f32 v36, v40, v41
	v_cvt_pk_bf16_f32 v37, v42, v43
	v_cvt_pk_bf16_f32 v38, v44, v45
	v_cvt_pk_bf16_f32 v39, v46, v47
	v_cvt_pk_bf16_f32 v40, v60, v61
	v_cvt_pk_bf16_f32 v41, v62, v63
	v_cvt_pk_bf16_f32 v42, v64, v65
	v_cvt_pk_bf16_f32 v43, v66, v67
	v_cvt_pk_bf16_f32 v44, v68, v69
	v_cvt_pk_bf16_f32 v45, v70, v71
	v_cvt_pk_bf16_f32 v46, v72, v73
	v_cvt_pk_bf16_f32 v47, v74, v75
	global_store_dwordx2 v[52:53], v[32:33], off
	global_store_dwordx2 v[52:53], v[34:35], off offset:512
	global_store_dwordx2 v[52:53], v[36:37], off offset:1024
	global_store_dwordx2 v[52:53], v[38:39], off offset:1536
	global_store_dwordx2 v[52:53], v[40:41], off offset:2048
	global_store_dwordx2 v[52:53], v[42:43], off offset:2560
	global_store_dwordx2 v[52:53], v[44:45], off offset:3072
	global_store_dwordx2 v[52:53], v[46:47], off offset:3584
	v_lshl_add_u64 v[52:53], v[52:53], 0, s[6:7]
	s_andn2_b64 exec, exec, s[8:9]
	s_cbranch_execnz .LBB0_821
